# R1 and PROJ epilogue stores: system-scope write-through (sc0 sc1) instead of agent-scope (sc1)
# speedup vs baseline: 1.0003x; 1.0003x over previous
.LBB0_631:
	v_lshl_add_u32 v145, s47, 10, v142
	ds_read2_b32 v[146:147], v145 offset1:16
	v_lshl_or_b32 v148, s27, 8, v143
	v_lshl_add_u32 v152, s26, 8, v140
	v_ashrrev_i32_e32 v149, 31, v148
	s_andn2_b64 vcc, exec, s[34:35]
	s_waitcnt lgkmcnt(0)
	v_pk_mul_f32 v[128:129], v[128:129], v[146:147] op_sel_hi:[1,0]
	v_pk_mul_f32 v[126:127], v[126:127], v[146:147] op_sel_hi:[1,0]
	v_pk_mul_f32 v[122:123], v[122:123], v[146:147] op_sel_hi:[1,0]
	v_pk_mul_f32 v[124:125], v[124:125], v[146:147] op_sel_hi:[1,0]
	v_cvt_pk_bf16_f32 v126, v126, v127
	v_cvt_pk_bf16_f32 v127, v128, v129
	v_cvt_pk_bf16_f32 v128, v122, v123
	v_mov_b64_e32 v[122:123], s[10:11]
	v_cvt_pk_bf16_f32 v129, v124, v125
	v_mad_i64_i32 v[150:151], s[26:27], v152, s23, v[122:123]
	v_lshlrev_b64 v[124:125], 1, v[148:149]
	v_lshl_add_u64 v[148:149], v[150:151], 0, v[124:125]
	global_store_dwordx4 v[148:149], v[126:129], off sc0 sc1
	v_pk_mul_f32 v[116:117], v[116:117], v[146:147] op_sel_hi:[1,0]
	v_pk_mul_f32 v[114:115], v[114:115], v[146:147] op_sel_hi:[1,0]
	v_pk_mul_f32 v[126:127], v[108:109], v[146:147] op_sel_hi:[1,0]
	v_pk_mul_f32 v[108:109], v[106:107], v[146:147] op_sel_hi:[1,0]
	v_cvt_pk_bf16_f32 v106, v114, v115
	v_cvt_pk_bf16_f32 v107, v116, v117
	v_cvt_pk_bf16_f32 v108, v108, v109
	v_cvt_pk_bf16_f32 v109, v126, v127
	v_or_b32_e32 v115, 16, v152
	v_mov_b32_e32 v114, v147
	global_store_dwordx4 v[148:149], v[106:109], off offset:256 sc0 sc1
	v_pk_mul_f32 v[110:111], v[110:111], v[114:115] op_sel_hi:[1,0]
	v_pk_mul_f32 v[112:113], v[112:113], v[114:115] op_sel_hi:[1,0]
	v_pk_mul_f32 v[108:109], v[120:121], v[114:115] op_sel_hi:[1,0]
	v_pk_mul_f32 v[106:107], v[118:119], v[114:115] op_sel_hi:[1,0]
	v_pk_mul_f32 v[102:103], v[102:103], v[114:115] op_sel_hi:[1,0]
	v_cvt_pk_bf16_f32 v106, v106, v107
	v_cvt_pk_bf16_f32 v107, v108, v109
	v_cvt_pk_bf16_f32 v108, v110, v111
	v_mad_i64_i32 v[110:111], s[26:27], v115, s23, v[122:123]
	v_cvt_pk_bf16_f32 v109, v112, v113
	v_lshl_add_u64 v[110:111], v[110:111], 0, v[124:125]
	global_store_dwordx4 v[110:111], v[106:109], off sc0 sc1
	v_pk_mul_f32 v[104:105], v[104:105], v[114:115] op_sel_hi:[1,0]
	s_nop 0
	v_pk_mul_f32 v[106:107], v[96:97], v[114:115] op_sel_hi:[1,0]
	v_pk_mul_f32 v[96:97], v[94:95], v[114:115] op_sel_hi:[1,0]
	v_cvt_pk_bf16_f32 v94, v102, v103
	ds_read2_b32 v[102:103], v145 offset0:32 offset1:48
	v_cvt_pk_bf16_f32 v95, v104, v105
	v_cvt_pk_bf16_f32 v96, v96, v97
	v_cvt_pk_bf16_f32 v97, v106, v107
	global_store_dwordx4 v[110:111], v[94:97], off offset:256 sc0 sc1
	v_or_b32_e32 v104, 32, v152
	s_waitcnt lgkmcnt(0)
	v_pk_mul_f32 v[84:85], v[84:85], v[102:103] op_sel_hi:[1,0]
	v_pk_mul_f32 v[94:95], v[100:101], v[102:103] op_sel_hi:[1,0]
	v_pk_mul_f32 v[96:97], v[98:99], v[102:103] op_sel_hi:[1,0]
	v_pk_mul_f32 v[98:99], v[92:93], v[102:103] op_sel_hi:[1,0]
	v_pk_mul_f32 v[92:93], v[90:91], v[102:103] op_sel_hi:[1,0]
	v_cvt_pk_bf16_f32 v91, v94, v95
	v_mad_i64_i32 v[94:95], s[26:27], v104, s23, v[122:123]
	v_cvt_pk_bf16_f32 v90, v96, v97
	v_cvt_pk_bf16_f32 v92, v92, v93
	v_cvt_pk_bf16_f32 v93, v98, v99
	v_lshl_add_u64 v[94:95], v[94:95], 0, v[124:125]
	global_store_dwordx4 v[94:95], v[90:93], off sc0 sc1
	v_pk_mul_f32 v[82:83], v[82:83], v[102:103] op_sel_hi:[1,0]
	s_nop 0
	v_pk_mul_f32 v[90:91], v[76:77], v[102:103] op_sel_hi:[1,0]
	v_pk_mul_f32 v[76:77], v[74:75], v[102:103] op_sel_hi:[1,0]
	v_cvt_pk_bf16_f32 v74, v82, v83
	v_cvt_pk_bf16_f32 v75, v84, v85
	v_cvt_pk_bf16_f32 v76, v76, v77
	v_cvt_pk_bf16_f32 v77, v90, v91
	v_or_b32_e32 v83, 48, v152
	v_mov_b32_e32 v82, v103
	global_store_dwordx4 v[94:95], v[74:77], off offset:256 sc0 sc1
	v_pk_mul_f32 v[78:79], v[78:79], v[82:83] op_sel_hi:[1,0]
	v_pk_mul_f32 v[80:81], v[80:81], v[82:83] op_sel_hi:[1,0]
	v_pk_mul_f32 v[76:77], v[88:89], v[82:83] op_sel_hi:[1,0]
	v_pk_mul_f32 v[74:75], v[86:87], v[82:83] op_sel_hi:[1,0]
	v_pk_mul_f32 v[70:71], v[70:71], v[82:83] op_sel_hi:[1,0]
	v_cvt_pk_bf16_f32 v74, v74, v75
	v_cvt_pk_bf16_f32 v75, v76, v77
	v_cvt_pk_bf16_f32 v76, v78, v79
	v_mad_i64_i32 v[78:79], s[26:27], v83, s23, v[122:123]
	v_cvt_pk_bf16_f32 v77, v80, v81
	v_lshl_add_u64 v[78:79], v[78:79], 0, v[124:125]
	global_store_dwordx4 v[78:79], v[74:77], off sc0 sc1
	v_pk_mul_f32 v[72:73], v[72:73], v[82:83] op_sel_hi:[1,0]
	s_nop 0
	v_pk_mul_f32 v[74:75], v[68:69], v[82:83] op_sel_hi:[1,0]
	v_pk_mul_f32 v[68:69], v[66:67], v[82:83] op_sel_hi:[1,0]
	v_cvt_pk_bf16_f32 v66, v70, v71
	ds_read2_b32 v[70:71], v145 offset0:128 offset1:144
	v_cvt_pk_bf16_f32 v67, v72, v73
	v_cvt_pk_bf16_f32 v68, v68, v69
	v_cvt_pk_bf16_f32 v69, v74, v75
	global_store_dwordx4 v[78:79], v[66:69], off offset:256 sc0 sc1
	s_waitcnt lgkmcnt(0)
	v_pk_mul_f32 v[62:63], v[62:63], v[70:71] op_sel_hi:[1,0]
	v_pk_mul_f32 v[64:65], v[64:65], v[70:71] op_sel_hi:[1,0]
	v_add_u32_e32 v68, 0x80, v152
	v_pk_mul_f32 v[66:67], v[60:61], v[70:71] op_sel_hi:[1,0]
	v_pk_mul_f32 v[60:61], v[58:59], v[70:71] op_sel_hi:[1,0]
	v_cvt_pk_bf16_f32 v58, v62, v63
	v_mad_i64_i32 v[62:63], s[26:27], v68, s23, v[122:123]
	v_cvt_pk_bf16_f32 v59, v64, v65
	v_cvt_pk_bf16_f32 v60, v60, v61
	v_cvt_pk_bf16_f32 v61, v66, v67
	v_lshl_add_u64 v[62:63], v[62:63], 0, v[124:125]
	global_store_dwordx4 v[62:63], v[58:61], off sc0 sc1
	v_pk_mul_f32 v[52:53], v[52:53], v[70:71] op_sel_hi:[1,0]
	v_pk_mul_f32 v[50:51], v[50:51], v[70:71] op_sel_hi:[1,0]
	v_pk_mul_f32 v[58:59], v[44:45], v[70:71] op_sel_hi:[1,0]
	v_pk_mul_f32 v[44:45], v[42:43], v[70:71] op_sel_hi:[1,0]
	v_cvt_pk_bf16_f32 v42, v50, v51
	v_cvt_pk_bf16_f32 v43, v52, v53
	v_cvt_pk_bf16_f32 v44, v44, v45
	v_cvt_pk_bf16_f32 v45, v58, v59
	v_add_u32_e32 v51, 0x90, v152
	v_mov_b32_e32 v50, v71
	global_store_dwordx4 v[62:63], v[42:45], off offset:256 sc0 sc1
	v_pk_mul_f32 v[46:47], v[46:47], v[50:51] op_sel_hi:[1,0]
	v_pk_mul_f32 v[48:49], v[48:49], v[50:51] op_sel_hi:[1,0]
	v_pk_mul_f32 v[44:45], v[56:57], v[50:51] op_sel_hi:[1,0]
	v_pk_mul_f32 v[42:43], v[54:55], v[50:51] op_sel_hi:[1,0]
	v_pk_mul_f32 v[38:39], v[38:39], v[50:51] op_sel_hi:[1,0]
	v_cvt_pk_bf16_f32 v42, v42, v43
	v_cvt_pk_bf16_f32 v43, v44, v45
	v_cvt_pk_bf16_f32 v44, v46, v47
	v_mad_i64_i32 v[46:47], s[26:27], v51, s23, v[122:123]
	v_cvt_pk_bf16_f32 v45, v48, v49
	v_lshl_add_u64 v[46:47], v[46:47], 0, v[124:125]
	global_store_dwordx4 v[46:47], v[42:45], off sc0 sc1
	v_pk_mul_f32 v[40:41], v[40:41], v[50:51] op_sel_hi:[1,0]
	s_nop 0
	v_pk_mul_f32 v[42:43], v[32:33], v[50:51] op_sel_hi:[1,0]
	v_pk_mul_f32 v[32:33], v[30:31], v[50:51] op_sel_hi:[1,0]
	v_cvt_pk_bf16_f32 v30, v38, v39
	ds_read2_b32 v[38:39], v145 offset0:160 offset1:176
	v_cvt_pk_bf16_f32 v31, v40, v41
	v_cvt_pk_bf16_f32 v32, v32, v33
	v_cvt_pk_bf16_f32 v33, v42, v43
	global_store_dwordx4 v[46:47], v[30:33], off offset:256 sc0 sc1
	v_add_u32_e32 v40, 0xa0, v152
	s_waitcnt lgkmcnt(0)
	v_pk_mul_f32 v[20:21], v[20:21], v[38:39] op_sel_hi:[1,0]
	v_pk_mul_f32 v[30:31], v[36:37], v[38:39] op_sel_hi:[1,0]
	v_pk_mul_f32 v[32:33], v[34:35], v[38:39] op_sel_hi:[1,0]
	v_pk_mul_f32 v[34:35], v[28:29], v[38:39] op_sel_hi:[1,0]
	v_pk_mul_f32 v[28:29], v[26:27], v[38:39] op_sel_hi:[1,0]
	v_cvt_pk_bf16_f32 v27, v30, v31
	v_mad_i64_i32 v[30:31], s[26:27], v40, s23, v[122:123]
	v_cvt_pk_bf16_f32 v26, v32, v33
	v_cvt_pk_bf16_f32 v28, v28, v29
	v_cvt_pk_bf16_f32 v29, v34, v35
	v_lshl_add_u64 v[30:31], v[30:31], 0, v[124:125]
	global_store_dwordx4 v[30:31], v[26:29], off sc0 sc1
	v_pk_mul_f32 v[18:19], v[18:19], v[38:39] op_sel_hi:[1,0]
	s_nop 0
	v_pk_mul_f32 v[26:27], v[12:13], v[38:39] op_sel_hi:[1,0]
	v_pk_mul_f32 v[12:13], v[10:11], v[38:39] op_sel_hi:[1,0]
	v_cvt_pk_bf16_f32 v10, v18, v19
	v_cvt_pk_bf16_f32 v11, v20, v21
	v_cvt_pk_bf16_f32 v12, v12, v13
	v_cvt_pk_bf16_f32 v13, v26, v27
	v_add_u32_e32 v19, 0xb0, v152
	v_mov_b32_e32 v18, v39
	global_store_dwordx4 v[30:31], v[10:13], off offset:256 sc0 sc1
	v_pk_mul_f32 v[14:15], v[14:15], v[18:19] op_sel_hi:[1,0]
	v_pk_mul_f32 v[16:17], v[16:17], v[18:19] op_sel_hi:[1,0]
	v_pk_mul_f32 v[12:13], v[24:25], v[18:19] op_sel_hi:[1,0]
	v_pk_mul_f32 v[10:11], v[22:23], v[18:19] op_sel_hi:[1,0]
	v_pk_mul_f32 v[8:9], v[8:9], v[18:19] op_sel_hi:[1,0]
	v_cvt_pk_bf16_f32 v10, v10, v11
	v_cvt_pk_bf16_f32 v11, v12, v13
	v_cvt_pk_bf16_f32 v12, v14, v15
	v_mad_i64_i32 v[14:15], s[26:27], v19, s23, v[122:123]
	v_cvt_pk_bf16_f32 v13, v16, v17
	v_lshl_add_u64 v[14:15], v[14:15], 0, v[124:125]
	global_store_dwordx4 v[14:15], v[10:13], off sc0 sc1
	v_pk_mul_f32 v[6:7], v[6:7], v[18:19] op_sel_hi:[1,0]
	s_mov_b64 s[26:27], -1
	v_pk_mul_f32 v[10:11], v[4:5], v[18:19] op_sel_hi:[1,0]
	v_pk_mul_f32 v[4:5], v[2:3], v[18:19] op_sel_hi:[1,0]
	v_cvt_pk_bf16_f32 v2, v6, v7
	v_cvt_pk_bf16_f32 v3, v8, v9
	v_cvt_pk_bf16_f32 v4, v4, v5
	v_cvt_pk_bf16_f32 v5, v10, v11
	global_store_dwordx4 v[14:15], v[2:5], off offset:256 sc0 sc1
	s_cbranch_vccnz .LBB0_624
	s_andn2_b64 vcc, exec, s[2:3]
	s_cbranch_vccnz .LBB0_623
	s_barrier
	s_branch .LBB0_623

.LBB0_815:
	v_lshl_add_u32 v150, s49, 10, v146
	ds_read2_b32 v[142:143], v150 offset1:16
	v_lshl_or_b32 v140, s31, 7, v147
	v_lshl_add_u32 v149, s30, 8, v144
	v_ashrrev_i32_e32 v141, 31, v140
	s_movk_i32 s15, 0x1600
	s_waitcnt lgkmcnt(0)
	v_pk_mul_f32 v[126:127], v[126:127], v[142:143] op_sel_hi:[1,0]
	v_pk_mul_f32 v[122:123], v[122:123], v[142:143] op_sel_hi:[1,0]
	v_mul_f32_e32 v151, 0xbfb8aa3b, v126
	v_exp_f32_e32 v151, v151
	v_pk_mul_f32 v[124:125], v[124:125], v[142:143] op_sel_hi:[1,0]
	v_pk_mul_f32 v[118:119], v[118:119], v[142:143] op_sel_hi:[1,0]
	v_pk_mul_f32 v[114:115], v[114:115], v[142:143] op_sel_hi:[1,0]
	v_add_f32_e32 v151, 1.0, v151
	v_rcp_f32_e32 v152, v151
	v_mul_f32_e32 v151, 0xbfb8aa3b, v127
	v_exp_f32_e32 v151, v151
	v_pk_mul_f32 v[116:117], v[116:117], v[142:143] op_sel_hi:[1,0]
	s_andn2_b64 vcc, exec, s[34:35]
	v_add_f32_e32 v151, 1.0, v151
	v_rcp_f32_e32 v153, v151
	s_nop 0
	v_pk_mul_f32 v[126:127], v[126:127], v[152:153]
	s_nop 0
	v_pk_mul_f32 v[122:123], v[122:123], v[126:127]
	v_pk_mul_f32 v[126:127], v[128:129], v[142:143] op_sel_hi:[1,0]
	s_nop 0
	v_mul_f32_e32 v128, 0xbfb8aa3b, v126
	v_mul_f32_e32 v129, 0xbfb8aa3b, v127
	v_exp_f32_e32 v128, v128
	v_exp_f32_e32 v129, v129
	v_add_f32_e32 v128, 1.0, v128
	v_add_f32_e32 v129, 1.0, v129
	v_rcp_f32_e32 v128, v128
	v_rcp_f32_e32 v129, v129
	s_nop 0
	v_pk_mul_f32 v[126:127], v[126:127], v[128:129]
	s_nop 0
	v_pk_mul_f32 v[124:125], v[124:125], v[126:127]
	v_mul_f32_e32 v126, 0xbfb8aa3b, v118
	v_mul_f32_e32 v127, 0xbfb8aa3b, v119
	v_exp_f32_e32 v126, v126
	v_exp_f32_e32 v127, v127
	v_add_f32_e32 v126, 1.0, v126
	v_add_f32_e32 v127, 1.0, v127
	v_rcp_f32_e32 v126, v126
	v_rcp_f32_e32 v127, v127
	s_nop 0
	v_pk_mul_f32 v[118:119], v[118:119], v[126:127]
	s_nop 0
	v_pk_mul_f32 v[114:115], v[114:115], v[118:119]
	v_pk_mul_f32 v[118:119], v[120:121], v[142:143] op_sel_hi:[1,0]
	s_nop 0
	v_mul_f32_e32 v120, 0xbfb8aa3b, v118
	v_mul_f32_e32 v121, 0xbfb8aa3b, v119
	v_exp_f32_e32 v120, v120
	v_exp_f32_e32 v121, v121
	v_add_f32_e32 v120, 1.0, v120
	v_add_f32_e32 v121, 1.0, v121
	v_rcp_f32_e32 v120, v120
	v_rcp_f32_e32 v121, v121
	s_nop 0
	v_pk_mul_f32 v[118:119], v[118:119], v[120:121]
	s_nop 0
	v_pk_mul_f32 v[116:117], v[116:117], v[118:119]
	v_cvt_pk_bf16_f32 v120, v114, v115
	v_mov_b64_e32 v[114:115], s[10:11]
	v_cvt_pk_bf16_f32 v118, v122, v123
	v_cvt_pk_bf16_f32 v121, v116, v117
	v_mad_i64_i32 v[122:123], s[30:31], v149, s15, v[114:115]
	v_lshlrev_b64 v[116:117], 1, v[140:141]
	v_cvt_pk_bf16_f32 v119, v124, v125
	v_lshl_add_u64 v[122:123], v[122:123], 0, v[116:117]
	global_store_dwordx4 v[122:123], v[118:121], off sc0 sc1
	s_nop 1
	v_mov_b32_e32 v118, v143
	v_pk_mul_f32 v[110:111], v[110:111], v[118:119] op_sel_hi:[1,0]
	s_nop 0
	v_mul_f32_e32 v119, 0xbfb8aa3b, v110
	v_exp_f32_e32 v119, v119
	s_nop 0
	v_add_f32_e32 v119, 1.0, v119
	v_rcp_f32_e32 v120, v119
	v_pk_mul_f32 v[106:107], v[106:107], v[118:119] op_sel_hi:[1,0]
	v_mul_f32_e32 v119, 0xbfb8aa3b, v111
	v_exp_f32_e32 v119, v119
	s_nop 0
	v_add_f32_e32 v119, 1.0, v119
	v_rcp_f32_e32 v121, v119
	v_pk_mul_f32 v[108:109], v[108:109], v[118:119] op_sel_hi:[1,0]
	v_pk_mul_f32 v[102:103], v[102:103], v[118:119] op_sel_hi:[1,0]
	v_pk_mul_f32 v[98:99], v[98:99], v[118:119] op_sel_hi:[1,0]
	v_pk_mul_f32 v[110:111], v[110:111], v[120:121]
	v_pk_mul_f32 v[100:101], v[100:101], v[118:119] op_sel_hi:[1,0]
	v_pk_mul_f32 v[106:107], v[106:107], v[110:111]
	v_pk_mul_f32 v[110:111], v[112:113], v[118:119] op_sel_hi:[1,0]
	s_nop 0
	v_mul_f32_e32 v112, 0xbfb8aa3b, v110
	v_mul_f32_e32 v113, 0xbfb8aa3b, v111
	v_exp_f32_e32 v112, v112
	v_exp_f32_e32 v113, v113
	v_add_f32_e32 v112, 1.0, v112
	v_add_f32_e32 v113, 1.0, v113
	v_rcp_f32_e32 v112, v112
	v_rcp_f32_e32 v113, v113
	s_nop 0
	v_pk_mul_f32 v[110:111], v[110:111], v[112:113]
	s_nop 0
	v_pk_mul_f32 v[108:109], v[108:109], v[110:111]
	v_mul_f32_e32 v110, 0xbfb8aa3b, v102
	v_mul_f32_e32 v111, 0xbfb8aa3b, v103
	v_exp_f32_e32 v110, v110
	v_exp_f32_e32 v111, v111
	v_add_f32_e32 v110, 1.0, v110
	v_add_f32_e32 v111, 1.0, v111
	v_rcp_f32_e32 v110, v110
	v_rcp_f32_e32 v111, v111
	s_nop 0
	v_pk_mul_f32 v[102:103], v[102:103], v[110:111]
	s_nop 0
	v_pk_mul_f32 v[102:103], v[98:99], v[102:103]
	v_pk_mul_f32 v[98:99], v[104:105], v[118:119] op_sel_hi:[1,0]
	v_or_b32_e32 v110, 16, v149
	v_mul_f32_e32 v104, 0xbfb8aa3b, v98
	v_mul_f32_e32 v105, 0xbfb8aa3b, v99
	v_exp_f32_e32 v104, v104
	v_exp_f32_e32 v105, v105
	v_add_f32_e32 v104, 1.0, v104
	v_add_f32_e32 v105, 1.0, v105
	v_rcp_f32_e32 v104, v104
	v_rcp_f32_e32 v105, v105
	s_nop 0
	v_pk_mul_f32 v[98:99], v[98:99], v[104:105]
	s_nop 0
	v_pk_mul_f32 v[104:105], v[100:101], v[98:99]
	v_cvt_pk_bf16_f32 v100, v102, v103
	v_mad_i64_i32 v[102:103], s[30:31], v110, s15, v[114:115]
	v_cvt_pk_bf16_f32 v98, v106, v107
	v_cvt_pk_bf16_f32 v99, v108, v109
	v_cvt_pk_bf16_f32 v101, v104, v105
	v_lshl_add_u64 v[102:103], v[102:103], 0, v[116:117]
	global_store_dwordx4 v[102:103], v[98:101], off sc0 sc1
	ds_read2_b32 v[98:99], v150 offset0:32 offset1:48
	s_waitcnt lgkmcnt(0)
	v_pk_mul_f32 v[94:95], v[94:95], v[98:99] op_sel_hi:[1,0]
	s_nop 0
	v_mul_f32_e32 v100, 0xbfb8aa3b, v94
	v_mul_f32_e32 v101, 0xbfb8aa3b, v95
	v_exp_f32_e32 v100, v100
	v_exp_f32_e32 v101, v101
	v_pk_mul_f32 v[90:91], v[90:91], v[98:99] op_sel_hi:[1,0]
	v_pk_mul_f32 v[92:93], v[92:93], v[98:99] op_sel_hi:[1,0]
	v_add_f32_e32 v100, 1.0, v100
	v_add_f32_e32 v101, 1.0, v101
	v_rcp_f32_e32 v100, v100
	v_rcp_f32_e32 v101, v101
	v_pk_mul_f32 v[86:87], v[86:87], v[98:99] op_sel_hi:[1,0]
	v_pk_mul_f32 v[82:83], v[82:83], v[98:99] op_sel_hi:[1,0]
	v_pk_mul_f32 v[84:85], v[84:85], v[98:99] op_sel_hi:[1,0]
	v_pk_mul_f32 v[94:95], v[94:95], v[100:101]
	s_nop 0
	v_pk_mul_f32 v[90:91], v[90:91], v[94:95]
	v_pk_mul_f32 v[94:95], v[96:97], v[98:99] op_sel_hi:[1,0]
	s_nop 0
	v_mul_f32_e32 v96, 0xbfb8aa3b, v94
	v_mul_f32_e32 v97, 0xbfb8aa3b, v95
	v_exp_f32_e32 v96, v96
	v_exp_f32_e32 v97, v97
	v_add_f32_e32 v96, 1.0, v96
	v_add_f32_e32 v97, 1.0, v97
	v_rcp_f32_e32 v96, v96
	v_rcp_f32_e32 v97, v97
	s_nop 0
	v_pk_mul_f32 v[94:95], v[94:95], v[96:97]
	s_nop 0
	v_pk_mul_f32 v[92:93], v[92:93], v[94:95]
	v_mul_f32_e32 v94, 0xbfb8aa3b, v86
	v_mul_f32_e32 v95, 0xbfb8aa3b, v87
	v_exp_f32_e32 v94, v94
	v_exp_f32_e32 v95, v95
	v_add_f32_e32 v94, 1.0, v94
	v_add_f32_e32 v95, 1.0, v95
	v_rcp_f32_e32 v94, v94
	v_rcp_f32_e32 v95, v95
	s_nop 0
	v_pk_mul_f32 v[86:87], v[86:87], v[94:95]
	s_nop 0
	v_pk_mul_f32 v[86:87], v[82:83], v[86:87]
	v_pk_mul_f32 v[82:83], v[88:89], v[98:99] op_sel_hi:[1,0]
	v_or_b32_e32 v94, 32, v149
	v_mul_f32_e32 v88, 0xbfb8aa3b, v82
	v_mul_f32_e32 v89, 0xbfb8aa3b, v83
	v_exp_f32_e32 v88, v88
	v_exp_f32_e32 v89, v89
	v_add_f32_e32 v88, 1.0, v88
	v_add_f32_e32 v89, 1.0, v89
	v_rcp_f32_e32 v88, v88
	v_rcp_f32_e32 v89, v89
	s_nop 0
	v_pk_mul_f32 v[82:83], v[82:83], v[88:89]
	s_nop 0
	v_pk_mul_f32 v[88:89], v[84:85], v[82:83]
	v_cvt_pk_bf16_f32 v84, v86, v87
	v_mad_i64_i32 v[86:87], s[30:31], v94, s15, v[114:115]
	v_cvt_pk_bf16_f32 v82, v90, v91
	v_cvt_pk_bf16_f32 v83, v92, v93
	v_cvt_pk_bf16_f32 v85, v88, v89
	v_lshl_add_u64 v[86:87], v[86:87], 0, v[116:117]
	global_store_dwordx4 v[86:87], v[82:85], off sc0 sc1
	s_nop 1
	v_mov_b32_e32 v82, v99
	v_pk_mul_f32 v[78:79], v[78:79], v[82:83] op_sel_hi:[1,0]
	s_nop 0
	v_mul_f32_e32 v83, 0xbfb8aa3b, v78
	v_exp_f32_e32 v83, v83
	s_nop 0
	v_add_f32_e32 v83, 1.0, v83
	v_rcp_f32_e32 v84, v83
	v_pk_mul_f32 v[74:75], v[74:75], v[82:83] op_sel_hi:[1,0]
	v_mul_f32_e32 v83, 0xbfb8aa3b, v79
	v_exp_f32_e32 v83, v83
	s_nop 0
	v_add_f32_e32 v83, 1.0, v83
	v_rcp_f32_e32 v85, v83
	v_pk_mul_f32 v[76:77], v[76:77], v[82:83] op_sel_hi:[1,0]
	v_pk_mul_f32 v[70:71], v[70:71], v[82:83] op_sel_hi:[1,0]
	v_pk_mul_f32 v[66:67], v[66:67], v[82:83] op_sel_hi:[1,0]
	v_pk_mul_f32 v[78:79], v[78:79], v[84:85]
	v_pk_mul_f32 v[68:69], v[68:69], v[82:83] op_sel_hi:[1,0]
	v_pk_mul_f32 v[74:75], v[74:75], v[78:79]
	v_pk_mul_f32 v[78:79], v[80:81], v[82:83] op_sel_hi:[1,0]
	s_nop 0
	v_mul_f32_e32 v80, 0xbfb8aa3b, v78
	v_mul_f32_e32 v81, 0xbfb8aa3b, v79
	v_exp_f32_e32 v80, v80
	v_exp_f32_e32 v81, v81
	v_add_f32_e32 v80, 1.0, v80
	v_add_f32_e32 v81, 1.0, v81
	v_rcp_f32_e32 v80, v80
	v_rcp_f32_e32 v81, v81
	s_nop 0
	v_pk_mul_f32 v[78:79], v[78:79], v[80:81]
	s_nop 0
	v_pk_mul_f32 v[76:77], v[76:77], v[78:79]
	v_mul_f32_e32 v78, 0xbfb8aa3b, v70
	v_mul_f32_e32 v79, 0xbfb8aa3b, v71
	v_exp_f32_e32 v78, v78
	v_exp_f32_e32 v79, v79
	v_add_f32_e32 v78, 1.0, v78
	v_add_f32_e32 v79, 1.0, v79
	v_rcp_f32_e32 v78, v78
	v_rcp_f32_e32 v79, v79
	s_nop 0
	v_pk_mul_f32 v[70:71], v[70:71], v[78:79]
	s_nop 0
	v_pk_mul_f32 v[70:71], v[66:67], v[70:71]
	v_pk_mul_f32 v[66:67], v[72:73], v[82:83] op_sel_hi:[1,0]
	v_or_b32_e32 v78, 48, v149
	v_mul_f32_e32 v72, 0xbfb8aa3b, v66
	v_mul_f32_e32 v73, 0xbfb8aa3b, v67
	v_exp_f32_e32 v72, v72
	v_exp_f32_e32 v73, v73
	v_add_f32_e32 v72, 1.0, v72
	v_add_f32_e32 v73, 1.0, v73
	v_rcp_f32_e32 v72, v72
	v_rcp_f32_e32 v73, v73
	s_nop 0
	v_pk_mul_f32 v[66:67], v[66:67], v[72:73]
	s_nop 0
	v_pk_mul_f32 v[72:73], v[68:69], v[66:67]
	v_cvt_pk_bf16_f32 v68, v70, v71
	v_mad_i64_i32 v[70:71], s[30:31], v78, s15, v[114:115]
	v_cvt_pk_bf16_f32 v66, v74, v75
	v_cvt_pk_bf16_f32 v67, v76, v77
	v_cvt_pk_bf16_f32 v69, v72, v73
	v_lshl_add_u64 v[70:71], v[70:71], 0, v[116:117]
	global_store_dwordx4 v[70:71], v[66:69], off sc0 sc1
	ds_read2_b32 v[66:67], v150 offset0:128 offset1:144
	v_add_u32_e32 v70, 0x80, v149
	s_waitcnt lgkmcnt(0)
	v_pk_mul_f32 v[62:63], v[62:63], v[66:67] op_sel_hi:[1,0]
	s_nop 0
	v_mul_f32_e32 v68, 0xbfb8aa3b, v62
	v_mul_f32_e32 v69, 0xbfb8aa3b, v63
	v_exp_f32_e32 v68, v68
	v_exp_f32_e32 v69, v69
	v_pk_mul_f32 v[58:59], v[58:59], v[66:67] op_sel_hi:[1,0]
	v_pk_mul_f32 v[60:61], v[60:61], v[66:67] op_sel_hi:[1,0]
	v_add_f32_e32 v68, 1.0, v68
	v_add_f32_e32 v69, 1.0, v69
	v_rcp_f32_e32 v68, v68
	v_rcp_f32_e32 v69, v69
	v_pk_mul_f32 v[54:55], v[54:55], v[66:67] op_sel_hi:[1,0]
	v_pk_mul_f32 v[50:51], v[50:51], v[66:67] op_sel_hi:[1,0]
	v_pk_mul_f32 v[52:53], v[52:53], v[66:67] op_sel_hi:[1,0]
	v_pk_mul_f32 v[62:63], v[62:63], v[68:69]
	s_nop 0
	v_pk_mul_f32 v[58:59], v[58:59], v[62:63]
	v_pk_mul_f32 v[62:63], v[64:65], v[66:67] op_sel_hi:[1,0]
	s_nop 0
	v_mul_f32_e32 v64, 0xbfb8aa3b, v62
	v_mul_f32_e32 v65, 0xbfb8aa3b, v63
	v_exp_f32_e32 v64, v64
	v_exp_f32_e32 v65, v65
	v_add_f32_e32 v64, 1.0, v64
	v_add_f32_e32 v65, 1.0, v65
	v_rcp_f32_e32 v64, v64
	v_rcp_f32_e32 v65, v65
	s_nop 0
	v_pk_mul_f32 v[62:63], v[62:63], v[64:65]
	s_nop 0
	v_pk_mul_f32 v[60:61], v[60:61], v[62:63]
	v_mul_f32_e32 v62, 0xbfb8aa3b, v54
	v_mul_f32_e32 v63, 0xbfb8aa3b, v55
	v_exp_f32_e32 v62, v62
	v_exp_f32_e32 v63, v63
	v_add_f32_e32 v62, 1.0, v62
	v_add_f32_e32 v63, 1.0, v63
	v_rcp_f32_e32 v62, v62
	v_rcp_f32_e32 v63, v63
	s_nop 0
	v_pk_mul_f32 v[54:55], v[54:55], v[62:63]
	s_nop 0
	v_pk_mul_f32 v[54:55], v[50:51], v[54:55]
	v_pk_mul_f32 v[50:51], v[56:57], v[66:67] op_sel_hi:[1,0]
	s_nop 0
	v_mul_f32_e32 v56, 0xbfb8aa3b, v50
	v_mul_f32_e32 v57, 0xbfb8aa3b, v51
	v_exp_f32_e32 v56, v56
	v_exp_f32_e32 v57, v57
	v_add_f32_e32 v56, 1.0, v56
	v_add_f32_e32 v57, 1.0, v57
	v_rcp_f32_e32 v56, v56
	v_rcp_f32_e32 v57, v57
	s_nop 0
	v_pk_mul_f32 v[50:51], v[50:51], v[56:57]
	s_nop 0
	v_pk_mul_f32 v[56:57], v[52:53], v[50:51]
	v_cvt_pk_bf16_f32 v52, v54, v55
	v_mad_i64_i32 v[54:55], s[30:31], v70, s15, v[114:115]
	v_cvt_pk_bf16_f32 v50, v58, v59
	v_cvt_pk_bf16_f32 v51, v60, v61
	v_cvt_pk_bf16_f32 v53, v56, v57
	v_lshl_add_u64 v[54:55], v[54:55], 0, v[116:117]
	global_store_dwordx4 v[54:55], v[50:53], off sc0 sc1
	s_nop 1
	v_mov_b32_e32 v50, v67
	v_pk_mul_f32 v[46:47], v[46:47], v[50:51] op_sel_hi:[1,0]
	s_nop 0
	v_mul_f32_e32 v51, 0xbfb8aa3b, v46
	v_exp_f32_e32 v51, v51
	s_nop 0
	v_add_f32_e32 v51, 1.0, v51
	v_rcp_f32_e32 v52, v51
	v_pk_mul_f32 v[42:43], v[42:43], v[50:51] op_sel_hi:[1,0]
	v_mul_f32_e32 v51, 0xbfb8aa3b, v47
	v_exp_f32_e32 v51, v51
	s_nop 0
	v_add_f32_e32 v51, 1.0, v51
	v_rcp_f32_e32 v53, v51
	v_pk_mul_f32 v[44:45], v[44:45], v[50:51] op_sel_hi:[1,0]
	v_pk_mul_f32 v[38:39], v[38:39], v[50:51] op_sel_hi:[1,0]
	v_pk_mul_f32 v[34:35], v[34:35], v[50:51] op_sel_hi:[1,0]
	v_pk_mul_f32 v[46:47], v[46:47], v[52:53]
	v_pk_mul_f32 v[36:37], v[36:37], v[50:51] op_sel_hi:[1,0]
	v_pk_mul_f32 v[42:43], v[42:43], v[46:47]
	v_pk_mul_f32 v[46:47], v[48:49], v[50:51] op_sel_hi:[1,0]
	s_nop 0
	v_mul_f32_e32 v48, 0xbfb8aa3b, v46
	v_mul_f32_e32 v49, 0xbfb8aa3b, v47
	v_exp_f32_e32 v48, v48
	v_exp_f32_e32 v49, v49
	v_add_f32_e32 v48, 1.0, v48
	v_add_f32_e32 v49, 1.0, v49
	v_rcp_f32_e32 v48, v48
	v_rcp_f32_e32 v49, v49
	s_nop 0
	v_pk_mul_f32 v[46:47], v[46:47], v[48:49]
	s_nop 0
	v_pk_mul_f32 v[44:45], v[44:45], v[46:47]
	v_mul_f32_e32 v46, 0xbfb8aa3b, v38
	v_mul_f32_e32 v47, 0xbfb8aa3b, v39
	v_exp_f32_e32 v46, v46
	v_exp_f32_e32 v47, v47
	v_add_f32_e32 v46, 1.0, v46
	v_add_f32_e32 v47, 1.0, v47
	v_rcp_f32_e32 v46, v46
	v_rcp_f32_e32 v47, v47
	s_nop 0
	v_pk_mul_f32 v[38:39], v[38:39], v[46:47]
	s_nop 0
	v_pk_mul_f32 v[38:39], v[34:35], v[38:39]
	v_pk_mul_f32 v[34:35], v[40:41], v[50:51] op_sel_hi:[1,0]
	v_add_u32_e32 v46, 0x90, v149
	v_mul_f32_e32 v40, 0xbfb8aa3b, v34
	v_mul_f32_e32 v41, 0xbfb8aa3b, v35
	v_exp_f32_e32 v40, v40
	v_exp_f32_e32 v41, v41
	v_add_f32_e32 v40, 1.0, v40
	v_add_f32_e32 v41, 1.0, v41
	v_rcp_f32_e32 v40, v40
	v_rcp_f32_e32 v41, v41
	s_nop 0
	v_pk_mul_f32 v[34:35], v[34:35], v[40:41]
	s_nop 0
	v_pk_mul_f32 v[40:41], v[36:37], v[34:35]
	v_cvt_pk_bf16_f32 v36, v38, v39
	v_mad_i64_i32 v[38:39], s[30:31], v46, s15, v[114:115]
	v_cvt_pk_bf16_f32 v34, v42, v43
	v_cvt_pk_bf16_f32 v35, v44, v45
	v_cvt_pk_bf16_f32 v37, v40, v41
	v_lshl_add_u64 v[38:39], v[38:39], 0, v[116:117]
	global_store_dwordx4 v[38:39], v[34:37], off sc0 sc1
	ds_read2_b32 v[34:35], v150 offset0:160 offset1:176
	s_waitcnt lgkmcnt(0)
	v_pk_mul_f32 v[30:31], v[30:31], v[34:35] op_sel_hi:[1,0]
	s_nop 0
	v_mul_f32_e32 v36, 0xbfb8aa3b, v30
	v_mul_f32_e32 v37, 0xbfb8aa3b, v31
	v_exp_f32_e32 v36, v36
	v_exp_f32_e32 v37, v37
	v_pk_mul_f32 v[26:27], v[26:27], v[34:35] op_sel_hi:[1,0]
	v_pk_mul_f32 v[28:29], v[28:29], v[34:35] op_sel_hi:[1,0]
	v_add_f32_e32 v36, 1.0, v36
	v_add_f32_e32 v37, 1.0, v37
	v_rcp_f32_e32 v36, v36
	v_rcp_f32_e32 v37, v37
	v_pk_mul_f32 v[22:23], v[22:23], v[34:35] op_sel_hi:[1,0]
	v_pk_mul_f32 v[18:19], v[18:19], v[34:35] op_sel_hi:[1,0]
	v_pk_mul_f32 v[20:21], v[20:21], v[34:35] op_sel_hi:[1,0]
	v_pk_mul_f32 v[30:31], v[30:31], v[36:37]
	s_nop 0
	v_pk_mul_f32 v[26:27], v[26:27], v[30:31]
	v_pk_mul_f32 v[30:31], v[32:33], v[34:35] op_sel_hi:[1,0]
	s_nop 0
	v_mul_f32_e32 v32, 0xbfb8aa3b, v30
	v_mul_f32_e32 v33, 0xbfb8aa3b, v31
	v_exp_f32_e32 v32, v32
	v_exp_f32_e32 v33, v33
	v_add_f32_e32 v32, 1.0, v32
	v_add_f32_e32 v33, 1.0, v33
	v_rcp_f32_e32 v32, v32
	v_rcp_f32_e32 v33, v33
	s_nop 0
	v_pk_mul_f32 v[30:31], v[30:31], v[32:33]
	s_nop 0
	v_pk_mul_f32 v[28:29], v[28:29], v[30:31]
	v_mul_f32_e32 v30, 0xbfb8aa3b, v22
	v_mul_f32_e32 v31, 0xbfb8aa3b, v23
	v_exp_f32_e32 v30, v30
	v_exp_f32_e32 v31, v31
	v_add_f32_e32 v30, 1.0, v30
	v_add_f32_e32 v31, 1.0, v31
	v_rcp_f32_e32 v30, v30
	v_rcp_f32_e32 v31, v31
	s_nop 0
	v_pk_mul_f32 v[22:23], v[22:23], v[30:31]
	s_nop 0
	v_pk_mul_f32 v[22:23], v[18:19], v[22:23]
	v_pk_mul_f32 v[18:19], v[24:25], v[34:35] op_sel_hi:[1,0]
	v_add_u32_e32 v30, 0xa0, v149
	v_mul_f32_e32 v24, 0xbfb8aa3b, v18
	v_mul_f32_e32 v25, 0xbfb8aa3b, v19
	v_exp_f32_e32 v24, v24
	v_exp_f32_e32 v25, v25
	v_add_f32_e32 v24, 1.0, v24
	v_add_f32_e32 v25, 1.0, v25
	v_rcp_f32_e32 v24, v24
	v_rcp_f32_e32 v25, v25
	s_nop 0
	v_pk_mul_f32 v[18:19], v[18:19], v[24:25]
	s_nop 0
	v_pk_mul_f32 v[24:25], v[20:21], v[18:19]
	v_cvt_pk_bf16_f32 v20, v22, v23
	v_mad_i64_i32 v[22:23], s[30:31], v30, s15, v[114:115]
	v_cvt_pk_bf16_f32 v18, v26, v27
	v_cvt_pk_bf16_f32 v19, v28, v29
	v_cvt_pk_bf16_f32 v21, v24, v25
	v_lshl_add_u64 v[22:23], v[22:23], 0, v[116:117]
	global_store_dwordx4 v[22:23], v[18:21], off sc0 sc1
	s_nop 1
	v_mov_b32_e32 v18, v35
	v_pk_mul_f32 v[14:15], v[14:15], v[18:19] op_sel_hi:[1,0]
	s_nop 0
	v_mul_f32_e32 v19, 0xbfb8aa3b, v14
	v_exp_f32_e32 v19, v19
	s_nop 0
	v_add_f32_e32 v19, 1.0, v19
	v_rcp_f32_e32 v20, v19
	v_pk_mul_f32 v[10:11], v[10:11], v[18:19] op_sel_hi:[1,0]
	v_mul_f32_e32 v19, 0xbfb8aa3b, v15
	v_exp_f32_e32 v19, v19
	s_nop 0
	v_add_f32_e32 v19, 1.0, v19
	v_rcp_f32_e32 v21, v19
	v_pk_mul_f32 v[12:13], v[12:13], v[18:19] op_sel_hi:[1,0]
	v_pk_mul_f32 v[6:7], v[6:7], v[18:19] op_sel_hi:[1,0]
	v_pk_mul_f32 v[2:3], v[2:3], v[18:19] op_sel_hi:[1,0]
	v_pk_mul_f32 v[14:15], v[14:15], v[20:21]
	v_pk_mul_f32 v[4:5], v[4:5], v[18:19] op_sel_hi:[1,0]
	v_pk_mul_f32 v[10:11], v[10:11], v[14:15]
	v_pk_mul_f32 v[14:15], v[16:17], v[18:19] op_sel_hi:[1,0]
	s_nop 0
	v_mul_f32_e32 v16, 0xbfb8aa3b, v14
	v_mul_f32_e32 v17, 0xbfb8aa3b, v15
	v_exp_f32_e32 v16, v16
	v_exp_f32_e32 v17, v17
	v_add_f32_e32 v16, 1.0, v16
	v_add_f32_e32 v17, 1.0, v17
	v_rcp_f32_e32 v16, v16
	v_rcp_f32_e32 v17, v17
	s_nop 0
	v_pk_mul_f32 v[14:15], v[14:15], v[16:17]
	s_nop 0
	v_pk_mul_f32 v[12:13], v[12:13], v[14:15]
	v_mul_f32_e32 v14, 0xbfb8aa3b, v6
	v_mul_f32_e32 v15, 0xbfb8aa3b, v7
	v_exp_f32_e32 v14, v14
	v_exp_f32_e32 v15, v15
	v_add_f32_e32 v14, 1.0, v14
	v_add_f32_e32 v15, 1.0, v15
	v_rcp_f32_e32 v14, v14
	v_rcp_f32_e32 v15, v15
	s_nop 0
	v_pk_mul_f32 v[6:7], v[6:7], v[14:15]
	s_nop 0
	v_pk_mul_f32 v[6:7], v[2:3], v[6:7]
	v_pk_mul_f32 v[2:3], v[8:9], v[18:19] op_sel_hi:[1,0]
	v_add_u32_e32 v14, 0xb0, v149
	v_mul_f32_e32 v8, 0xbfb8aa3b, v2
	v_mul_f32_e32 v9, 0xbfb8aa3b, v3
	v_exp_f32_e32 v8, v8
	v_exp_f32_e32 v9, v9
	v_add_f32_e32 v8, 1.0, v8
	v_add_f32_e32 v9, 1.0, v9
	v_rcp_f32_e32 v8, v8
	v_rcp_f32_e32 v9, v9
	s_nop 0
	v_pk_mul_f32 v[2:3], v[2:3], v[8:9]
	s_nop 0
	v_pk_mul_f32 v[8:9], v[4:5], v[2:3]
	v_cvt_pk_bf16_f32 v4, v6, v7
	v_mad_i64_i32 v[6:7], s[30:31], v14, s15, v[114:115]
	v_cvt_pk_bf16_f32 v2, v10, v11
	v_cvt_pk_bf16_f32 v3, v12, v13
	v_cvt_pk_bf16_f32 v5, v8, v9
	v_lshl_add_u64 v[6:7], v[6:7], 0, v[116:117]
	s_mov_b64 s[30:31], -1
	global_store_dwordx4 v[6:7], v[2:5], off sc0 sc1
	s_cbranch_vccnz .LBB0_808
	s_andn2_b64 vcc, exec, s[8:9]
	s_cbranch_vccnz .LBB0_807
	s_barrier
	s_branch .LBB0_807
